# grid barrier: each arriving workgroup leader starts an L2 write-back on arrival so the XCD's last arriver finds little dirty data
# baseline (speedup 1.0000x reference)
; __device__ __forceinline__ void xcd_barrier(unsigned* bar_, volatile LAS unsigned* st_, int tid) {
;     ...
;   if (tid == 0) {
;     unsigned* bar = b.bar;
;     __builtin_amdgcn_s_waitcnt(0);
;     unsigned nloc = b.st[0], nx = b.st[1];
;     if (nloc == 0u) { xcd_barrier_complete(bar, b.x, nloc, nx); b.st[0] = nloc; b.st[1] = nx; }
.LBB0_997:
	s_waitcnt vmcnt(0) expcnt(0) lgkmcnt(0)
	buffer_wbl2 sc1
	ds_read_b32 v3, v1
	ds_read_b32 v2, v1 offset:4
	s_and_b32 s2, s2, 15
	s_waitcnt lgkmcnt(1)
	v_cmp_ne_u32_e32 vcc, 0, v3
	s_cbranch_vccnz .LBB0_1012
	s_mov_b32 s10, 1
	s_branch .LBB0_1000
